# EpiBf16 epilogues (GEMM-in, up) software-pipelined: groups list-scheduled so up to 3 groups of ds_bpermute are in flight, counted lgkmcnt (on v13)
# baseline (speedup 1.0000x reference)
; __device__ __forceinline__ unsigned cvt_pk_bf16(float lo, float hi) { unsigned r; asm volatile("v_cvt_pk_bf16_f32 %0, %1, %2" : "=v"(r) : "v"(lo), "v"(hi)); return r; }
;     __device__ __forceinline__ void operator()(const f32x4 (&acc)[2][2][4][2], const Unit& u, int wr, int wc, int fr, int fq) const {
;         const int lane = fr + 16 * fq, r2 = lane >> 2, q2 = lane & 3;
;         const int src4 = (r2 + 16 * q2) << 2;
;         const int row0 = u.pm * BM + wr * 64 + r2; const int col0 = u.pn * BM + wc * 32 + 8 * q2;
; #pragma unroll
;         for (int ai = 0; ai < 2; ++ai)
; #pragma unroll
;             for (int m = 0; m < 4; ++m) { bf16_t* rowp = O + (size_t)(row0 + ai * HALF + m * 16) * ldc + col0;
; #pragma unroll
;                 for (int bj = 0; bj < 2; ++bj) { f32x4 v0 = acc[ai][bj][m][0], v1 = acc[ai][bj][m][1];
;                     if (ACT == 1) {
; #pragma unroll
;                         for (int j = 0; j < 4; ++j) { const float a = fmaxf(v0[j], 0.f), b = fmaxf(v1[j], 0.f); v0[j] = a * a; v1[j] = b * b; } }
;                     u32x4 w; w.x = cvt_pk_bf16(v0[0], v0[1]); w.y = cvt_pk_bf16(v0[2], v0[3]); w.z = cvt_pk_bf16(v1[0], v1[1]); w.w = cvt_pk_bf16(v1[2], v1[3]);
;                     w.x = (unsigned)__builtin_amdgcn_ds_bpermute(src4, (int)w.x); w.y = (unsigned)__builtin_amdgcn_ds_bpermute(src4, (int)w.y);
;                     w.z = (unsigned)__builtin_amdgcn_ds_bpermute(src4, (int)w.z); w.w = (unsigned)__builtin_amdgcn_ds_bpermute(src4, (int)w.w);
;                     *(u32x4*)(rowp + bj * HALF) = w; } }
.LBB0_255:
	v_cvt_pk_bf16_f32 v128, v128, v129
	v_cvt_pk_bf16_f32 v129, v130, v131
	v_cvt_pk_bf16_f32 v124, v124, v125
	v_cvt_pk_bf16_f32 v125, v126, v127
	ds_bpermute_b32 v126, v143, v128
	ds_bpermute_b32 v127, v143, v129
	ds_bpermute_b32 v128, v143, v124
	ds_bpermute_b32 v129, v143, v125
	v_lshl_or_b32 v156, s50, 8, v145
	v_lshl_add_u32 v147, s51, 8, v144
	v_ashrrev_i32_e32 v157, 31, v156
	v_mov_b64_e32 v[140:141], s[8:9]
	v_mad_i64_i32 v[130:131], s[20:21], v147, s77, v[140:141]
	v_lshlrev_b64 v[124:125], 1, v[156:157]
	v_lshl_add_u64 v[130:131], v[130:131], 0, v[124:125]
	v_cvt_pk_bf16_f32 v116, v116, v117
	v_cvt_pk_bf16_f32 v117, v118, v119
	v_cvt_pk_bf16_f32 v118, v108, v109
	v_cvt_pk_bf16_f32 v111, v110, v111
	ds_bpermute_b32 v108, v143, v116
	ds_bpermute_b32 v109, v143, v117
	ds_bpermute_b32 v110, v143, v118
	ds_bpermute_b32 v111, v143, v111
	s_andn2_b64 vcc, exec, s[0:1]
	s_mov_b64 s[0:1], -1
	v_cvt_pk_bf16_f32 v100, v100, v101
	v_cvt_pk_bf16_f32 v101, v102, v103
	v_cvt_pk_bf16_f32 v102, v92, v93
	v_cvt_pk_bf16_f32 v95, v94, v95
	ds_bpermute_b32 v92, v143, v100
	ds_bpermute_b32 v93, v143, v101
	ds_bpermute_b32 v94, v143, v102
	ds_bpermute_b32 v95, v143, v95
	s_waitcnt lgkmcnt(8)
	global_store_dwordx4 v[130:131], v[126:129], off
	s_nop 1
	v_cvt_pk_bf16_f32 v84, v84, v85
	v_cvt_pk_bf16_f32 v85, v86, v87
	v_cvt_pk_bf16_f32 v86, v76, v77
	v_cvt_pk_bf16_f32 v79, v78, v79
	ds_bpermute_b32 v76, v143, v84
	ds_bpermute_b32 v77, v143, v85
	ds_bpermute_b32 v78, v143, v86
	ds_bpermute_b32 v79, v143, v79
	s_waitcnt lgkmcnt(8)
	global_store_dwordx4 v[130:131], v[108:111], off offset:256
	s_nop 1
	v_cvt_pk_bf16_f32 v108, v120, v121
	v_cvt_pk_bf16_f32 v109, v122, v123
	v_cvt_pk_bf16_f32 v110, v112, v113
	v_cvt_pk_bf16_f32 v111, v114, v115
	ds_bpermute_b32 v108, v143, v108
	ds_bpermute_b32 v109, v143, v109
	ds_bpermute_b32 v110, v143, v110
	ds_bpermute_b32 v111, v143, v111
	v_or_b32_e32 v112, 16, v147
	v_mad_i64_i32 v[112:113], s[20:21], v112, s77, v[140:141]
	v_lshl_add_u64 v[112:113], v[112:113], 0, v[124:125]
	s_waitcnt lgkmcnt(8)
	global_store_dwordx4 v[112:113], v[92:95], off offset:256
	s_nop 1
	v_cvt_pk_bf16_f32 v92, v104, v105
	v_cvt_pk_bf16_f32 v93, v106, v107
	v_cvt_pk_bf16_f32 v94, v96, v97
	v_cvt_pk_bf16_f32 v95, v98, v99
	ds_bpermute_b32 v92, v143, v92
	ds_bpermute_b32 v93, v143, v93
	ds_bpermute_b32 v94, v143, v94
	ds_bpermute_b32 v95, v143, v95
	v_or_b32_e32 v96, 32, v147
	v_mad_i64_i32 v[96:97], s[20:21], v96, s77, v[140:141]
	v_lshl_add_u64 v[96:97], v[96:97], 0, v[124:125]
	s_waitcnt lgkmcnt(8)
	global_store_dwordx4 v[96:97], v[76:79], off offset:256
	s_nop 1
	v_cvt_pk_bf16_f32 v76, v88, v89
	v_cvt_pk_bf16_f32 v77, v90, v91
	v_cvt_pk_bf16_f32 v78, v80, v81
	v_cvt_pk_bf16_f32 v79, v82, v83
	ds_bpermute_b32 v76, v143, v76
	ds_bpermute_b32 v77, v143, v77
	ds_bpermute_b32 v78, v143, v78
	ds_bpermute_b32 v79, v143, v79
	v_or_b32_e32 v80, 48, v147
	v_mad_i64_i32 v[80:81], s[20:21], v80, s77, v[140:141]
	v_lshl_add_u64 v[80:81], v[80:81], 0, v[124:125]
	s_waitcnt lgkmcnt(8)
	global_store_dwordx4 v[112:113], v[108:111], off
	s_nop 1
	v_cvt_pk_bf16_f32 v72, v72, v73
	v_cvt_pk_bf16_f32 v73, v74, v75
	v_cvt_pk_bf16_f32 v74, v68, v69
	v_cvt_pk_bf16_f32 v71, v70, v71
	ds_bpermute_b32 v68, v143, v72
	ds_bpermute_b32 v69, v143, v73
	ds_bpermute_b32 v70, v143, v74
	ds_bpermute_b32 v71, v143, v71
	s_waitcnt lgkmcnt(8)
	global_store_dwordx4 v[96:97], v[92:95], off
	s_nop 1
	v_cvt_pk_bf16_f32 v64, v64, v65
	v_cvt_pk_bf16_f32 v65, v66, v67
	v_cvt_pk_bf16_f32 v66, v60, v61
	v_cvt_pk_bf16_f32 v63, v62, v63
	ds_bpermute_b32 v60, v143, v64
	ds_bpermute_b32 v61, v143, v65
	ds_bpermute_b32 v62, v143, v66
	ds_bpermute_b32 v63, v143, v63
	v_add_u32_e32 v64, 0x80, v147
	v_mad_i64_i32 v[64:65], s[20:21], v64, s77, v[140:141]
	v_lshl_add_u64 v[64:65], v[64:65], 0, v[124:125]
	s_waitcnt lgkmcnt(8)
	global_store_dwordx4 v[80:81], v[76:79], off
	s_nop 1
	v_cvt_pk_bf16_f32 v52, v52, v53
	v_cvt_pk_bf16_f32 v53, v54, v55
	v_cvt_pk_bf16_f32 v54, v44, v45
	v_cvt_pk_bf16_f32 v47, v46, v47
	ds_bpermute_b32 v44, v143, v52
	ds_bpermute_b32 v45, v143, v53
	ds_bpermute_b32 v46, v143, v54
	ds_bpermute_b32 v47, v143, v47
	s_waitcnt lgkmcnt(8)
	global_store_dwordx4 v[80:81], v[68:71], off offset:256
	s_nop 1
	v_cvt_pk_bf16_f32 v36, v36, v37
	v_cvt_pk_bf16_f32 v37, v38, v39
	v_cvt_pk_bf16_f32 v38, v28, v29
	v_cvt_pk_bf16_f32 v31, v30, v31
	ds_bpermute_b32 v28, v143, v36
	ds_bpermute_b32 v29, v143, v37
	ds_bpermute_b32 v30, v143, v38
	ds_bpermute_b32 v31, v143, v31
	s_waitcnt lgkmcnt(8)
	global_store_dwordx4 v[64:65], v[60:63], off
	s_nop 1
	v_cvt_pk_bf16_f32 v20, v20, v21
	v_cvt_pk_bf16_f32 v21, v22, v23
	v_cvt_pk_bf16_f32 v22, v12, v13
	v_cvt_pk_bf16_f32 v15, v14, v15
	ds_bpermute_b32 v12, v143, v20
	ds_bpermute_b32 v13, v143, v21
	ds_bpermute_b32 v14, v143, v22
	ds_bpermute_b32 v15, v143, v15
	s_waitcnt lgkmcnt(8)
	global_store_dwordx4 v[64:65], v[44:47], off offset:256
	s_nop 1
	v_cvt_pk_bf16_f32 v44, v56, v57
	v_cvt_pk_bf16_f32 v45, v58, v59
	v_cvt_pk_bf16_f32 v46, v48, v49
	v_cvt_pk_bf16_f32 v47, v50, v51
	ds_bpermute_b32 v44, v143, v44
	ds_bpermute_b32 v45, v143, v45
	ds_bpermute_b32 v46, v143, v46
	ds_bpermute_b32 v47, v143, v47
	v_add_u32_e32 v48, 0x90, v147
	v_mad_i64_i32 v[48:49], s[20:21], v48, s77, v[140:141]
	v_lshl_add_u64 v[48:49], v[48:49], 0, v[124:125]
	s_waitcnt lgkmcnt(8)
	global_store_dwordx4 v[48:49], v[28:31], off offset:256
	s_nop 1
	v_cvt_pk_bf16_f32 v28, v40, v41
	v_cvt_pk_bf16_f32 v29, v42, v43
	v_cvt_pk_bf16_f32 v30, v32, v33
	v_cvt_pk_bf16_f32 v31, v34, v35
	ds_bpermute_b32 v28, v143, v28
	ds_bpermute_b32 v29, v143, v29
	ds_bpermute_b32 v30, v143, v30
	ds_bpermute_b32 v31, v143, v31
	v_add_u32_e32 v32, 0xa0, v147
	v_mad_i64_i32 v[32:33], s[20:21], v32, s77, v[140:141]
	v_lshl_add_u64 v[32:33], v[32:33], 0, v[124:125]
	s_waitcnt lgkmcnt(8)
	global_store_dwordx4 v[32:33], v[12:15], off offset:256
	s_nop 1
	v_cvt_pk_bf16_f32 v12, v24, v25
	v_cvt_pk_bf16_f32 v13, v26, v27
	v_cvt_pk_bf16_f32 v14, v16, v17
	v_cvt_pk_bf16_f32 v15, v18, v19
	ds_bpermute_b32 v12, v143, v12
	ds_bpermute_b32 v13, v143, v13
	ds_bpermute_b32 v14, v143, v14
	ds_bpermute_b32 v15, v143, v15
	v_add_u32_e32 v16, 0xb0, v147
	v_mad_i64_i32 v[16:17], s[20:21], v16, s77, v[140:141]
	v_lshl_add_u64 v[16:17], v[16:17], 0, v[124:125]
	s_waitcnt lgkmcnt(8)
	global_store_dwordx4 v[48:49], v[44:47], off
	s_nop 1
	v_cvt_pk_bf16_f32 v4, v4, v5
	v_cvt_pk_bf16_f32 v5, v6, v7
	v_cvt_pk_bf16_f32 v6, v0, v1
	v_cvt_pk_bf16_f32 v3, v2, v3
	ds_bpermute_b32 v0, v143, v4
	ds_bpermute_b32 v1, v143, v5
	ds_bpermute_b32 v2, v143, v6
	ds_bpermute_b32 v3, v143, v3
	s_waitcnt lgkmcnt(8)
	global_store_dwordx4 v[32:33], v[28:31], off
	s_nop 1
	s_waitcnt lgkmcnt(4)
	global_store_dwordx4 v[16:17], v[12:15], off
	s_nop 1
	s_waitcnt lgkmcnt(0)
	global_store_dwordx4 v[16:17], v[0:3], off offset:256
	s_nop 1
	s_cbranch_vccnz .LBB0_248
	s_andn2_b64 vcc, exec, s[6:7]
	s_cbranch_vccnz .LBB0_247
	s_barrier
	s_branch .LBB0_247

; __device__ __forceinline__ unsigned cvt_pk_bf16(float lo, float hi) { unsigned r; asm volatile("v_cvt_pk_bf16_f32 %0, %1, %2" : "=v"(r) : "v"(lo), "v"(hi)); return r; }
;     __device__ __forceinline__ void operator()(const f32x4 (&acc)[2][2][4][2], const Unit& u, int wr, int wc, int fr, int fq) const {
;     ...
;             for (int m = 0; m < 4; ++m) { bf16_t* rowp = O + (size_t)(row0 + ai * HALF + m * 16) * ldc + col0;
; #pragma unroll
;                 for (int bj = 0; bj < 2; ++bj) { f32x4 v0 = acc[ai][bj][m][0], v1 = acc[ai][bj][m][1];
;                     if (ACT == 1) {
; #pragma unroll
;                         for (int j = 0; j < 4; ++j) { const float a = fmaxf(v0[j], 0.f), b = fmaxf(v1[j], 0.f); v0[j] = a * a; v1[j] = b * b; } }
;                     u32x4 w; w.x = cvt_pk_bf16(v0[0], v0[1]); w.y = cvt_pk_bf16(v0[2], v0[3]); w.z = cvt_pk_bf16(v1[0], v1[1]); w.w = cvt_pk_bf16(v1[2], v1[3]);
;                     w.x = (unsigned)__builtin_amdgcn_ds_bpermute(src4, (int)w.x); w.y = (unsigned)__builtin_amdgcn_ds_bpermute(src4, (int)w.y);
;                     w.z = (unsigned)__builtin_amdgcn_ds_bpermute(src4, (int)w.z); w.w = (unsigned)__builtin_amdgcn_ds_bpermute(src4, (int)w.w);
;                     *(u32x4*)(rowp + bj * HALF) = w; } }
.LBB0_1197:
	v_max_f32_e32 v128, v128, v128
	v_max_f32_e32 v129, v129, v129
	v_max_f32_e32 v128, 0, v128
	v_max_f32_e32 v124, v124, v124
	v_max_f32_e32 v129, 0, v129
	v_max_f32_e32 v125, v125, v125
	v_max_f32_e32 v130, v130, v130
	v_max_f32_e32 v131, v131, v131
	v_max_f32_e32 v124, 0, v124
	v_mul_f32_e32 v128, v128, v128
	v_max_f32_e32 v125, 0, v125
	v_mul_f32_e32 v129, v129, v129
	v_max_f32_e32 v130, 0, v130
	v_max_f32_e32 v126, v126, v126
	v_max_f32_e32 v131, 0, v131
	v_max_f32_e32 v127, v127, v127
	v_mul_f32_e32 v124, v124, v124
	v_mul_f32_e32 v125, v125, v125
	v_max_f32_e32 v126, 0, v126
	v_mul_f32_e32 v130, v130, v130
	v_max_f32_e32 v127, 0, v127
	v_mul_f32_e32 v131, v131, v131
	v_cvt_pk_bf16_f32 v128, v128, v129
	v_cvt_pk_bf16_f32 v129, v130, v131
	v_lshl_add_u32 v140, s61, 8, v144
	v_mul_f32_e32 v126, v126, v126
	v_mul_f32_e32 v127, v127, v127
	v_cvt_pk_bf16_f32 v124, v124, v125
	v_cvt_pk_bf16_f32 v125, v126, v127
	ds_bpermute_b32 v128, v143, v128
	ds_bpermute_b32 v129, v143, v129
	ds_bpermute_b32 v130, v143, v124
	ds_bpermute_b32 v131, v143, v125
	v_lshl_or_b32 v156, s60, 8, v145
	v_ashrrev_i32_e32 v141, 31, v140
	v_ashrrev_i32_e32 v157, 31, v156
	v_lshlrev_b64 v[124:125], 13, v[140:141]
	v_max_f32_e32 v120, v120, v120
	v_max_f32_e32 v121, v121, v121
	v_max_f32_e32 v122, v122, v122
	v_max_f32_e32 v119, v119, v119
	v_lshl_add_u64 v[124:125], s[12:13], 0, v[124:125]
	v_lshlrev_b64 v[126:127], 1, v[156:157]
	v_max_f32_e32 v120, 0, v120
	v_max_f32_e32 v116, v116, v116
	v_max_f32_e32 v121, 0, v121
	v_max_f32_e32 v117, v117, v117
	v_max_f32_e32 v122, 0, v122
	v_max_f32_e32 v118, v118, v118
	v_max_f32_e32 v123, v123, v123
	v_max_f32_e32 v119, 0, v119
	v_lshl_add_u64 v[124:125], v[124:125], 0, v[126:127]
	v_max_f32_e32 v116, 0, v116
	v_mul_f32_e32 v120, v120, v120
	v_max_f32_e32 v117, 0, v117
	v_mul_f32_e32 v121, v121, v121
	v_max_f32_e32 v118, 0, v118
	v_mul_f32_e32 v122, v122, v122
	v_max_f32_e32 v123, 0, v123
	v_mul_f32_e32 v119, v119, v119
	v_mul_f32_e32 v116, v116, v116
	v_mul_f32_e32 v117, v117, v117
	v_mul_f32_e32 v118, v118, v118
	v_mul_f32_e32 v123, v123, v123
	v_cvt_pk_bf16_f32 v120, v120, v121
	v_cvt_pk_bf16_f32 v121, v122, v123
	v_cvt_pk_bf16_f32 v122, v116, v117
	v_cvt_pk_bf16_f32 v119, v118, v119
	ds_bpermute_b32 v116, v143, v120
	ds_bpermute_b32 v117, v143, v121
	ds_bpermute_b32 v118, v143, v122
	ds_bpermute_b32 v119, v143, v119
	v_max_f32_e32 v112, v112, v112
	v_max_f32_e32 v113, v113, v113
	v_max_f32_e32 v114, v114, v114
	v_max_f32_e32 v111, v111, v111
	v_max_f32_e32 v112, 0, v112
	v_max_f32_e32 v108, v108, v108
	v_max_f32_e32 v113, 0, v113
	v_max_f32_e32 v109, v109, v109
	v_max_f32_e32 v114, 0, v114
	v_max_f32_e32 v110, v110, v110
	v_max_f32_e32 v115, v115, v115
	v_max_f32_e32 v111, 0, v111
	v_max_f32_e32 v108, 0, v108
	v_mul_f32_e32 v112, v112, v112
	v_max_f32_e32 v109, 0, v109
	v_mul_f32_e32 v113, v113, v113
	v_max_f32_e32 v110, 0, v110
	v_mul_f32_e32 v114, v114, v114
	v_max_f32_e32 v115, 0, v115
	v_mul_f32_e32 v111, v111, v111
	s_waitcnt lgkmcnt(4)
	global_store_dwordx4 v[124:125], v[128:131], off
	s_nop 1
	s_waitcnt lgkmcnt(0)
	global_store_dwordx4 v[124:125], v[116:119], off offset:256
	s_nop 1
	v_mul_f32_e32 v108, v108, v108
	v_mul_f32_e32 v109, v109, v109
	v_mul_f32_e32 v110, v110, v110
	v_mul_f32_e32 v115, v115, v115
	v_cvt_pk_bf16_f32 v112, v112, v113
	v_cvt_pk_bf16_f32 v113, v114, v115
	v_cvt_pk_bf16_f32 v114, v108, v109
	v_cvt_pk_bf16_f32 v111, v110, v111
	v_or_b32_e32 v116, 16, v140
	ds_bpermute_b32 v108, v143, v112
	ds_bpermute_b32 v109, v143, v113
	ds_bpermute_b32 v110, v143, v114
	ds_bpermute_b32 v111, v143, v111
	v_ashrrev_i32_e32 v117, 31, v116
	v_lshlrev_b64 v[112:113], 13, v[116:117]
	v_max_f32_e32 v104, v104, v104
	v_max_f32_e32 v105, v105, v105
	v_max_f32_e32 v106, v106, v106
	v_max_f32_e32 v103, v103, v103
	v_lshl_add_u64 v[112:113], s[12:13], 0, v[112:113]
	v_max_f32_e32 v104, 0, v104
	v_max_f32_e32 v100, v100, v100
	v_max_f32_e32 v105, 0, v105
	v_max_f32_e32 v101, v101, v101
	v_max_f32_e32 v106, 0, v106
	v_max_f32_e32 v102, v102, v102
	v_max_f32_e32 v107, v107, v107
	v_max_f32_e32 v103, 0, v103
	v_lshl_add_u64 v[112:113], v[112:113], 0, v[126:127]
	v_max_f32_e32 v100, 0, v100
	v_mul_f32_e32 v104, v104, v104
	v_max_f32_e32 v101, 0, v101
	v_mul_f32_e32 v105, v105, v105
	v_max_f32_e32 v102, 0, v102
	v_mul_f32_e32 v106, v106, v106
	v_max_f32_e32 v107, 0, v107
	v_mul_f32_e32 v103, v103, v103
	v_mul_f32_e32 v100, v100, v100
	v_mul_f32_e32 v101, v101, v101
	v_mul_f32_e32 v102, v102, v102
	v_mul_f32_e32 v107, v107, v107
	v_cvt_pk_bf16_f32 v104, v104, v105
	v_cvt_pk_bf16_f32 v105, v106, v107
	v_cvt_pk_bf16_f32 v106, v100, v101
	v_cvt_pk_bf16_f32 v103, v102, v103
	ds_bpermute_b32 v100, v143, v104
	ds_bpermute_b32 v101, v143, v105
	ds_bpermute_b32 v102, v143, v106
	ds_bpermute_b32 v103, v143, v103
	v_max_f32_e32 v96, v96, v96
	v_max_f32_e32 v97, v97, v97
	v_max_f32_e32 v98, v98, v98
	v_max_f32_e32 v95, v95, v95
	v_max_f32_e32 v96, 0, v96
	v_max_f32_e32 v92, v92, v92
	v_max_f32_e32 v97, 0, v97
	v_max_f32_e32 v93, v93, v93
	v_max_f32_e32 v98, 0, v98
	v_max_f32_e32 v94, v94, v94
	v_max_f32_e32 v99, v99, v99
	v_max_f32_e32 v95, 0, v95
	v_max_f32_e32 v92, 0, v92
	v_mul_f32_e32 v96, v96, v96
	v_max_f32_e32 v93, 0, v93
	v_mul_f32_e32 v97, v97, v97
	v_max_f32_e32 v94, 0, v94
	v_mul_f32_e32 v98, v98, v98
	v_max_f32_e32 v99, 0, v99
	v_mul_f32_e32 v95, v95, v95
	s_waitcnt lgkmcnt(4)
	global_store_dwordx4 v[112:113], v[108:111], off
	s_nop 1
	s_waitcnt lgkmcnt(0)
; __device__ __forceinline__ unsigned cvt_pk_bf16(float lo, float hi) { unsigned r; asm volatile("v_cvt_pk_bf16_f32 %0, %1, %2" : "=v"(r) : "v"(lo), "v"(hi)); return r; }
;     __device__ __forceinline__ void operator()(const f32x4 (&acc)[2][2][4][2], const Unit& u, int wr, int wc, int fr, int fq) const {
;     ...
;             for (int m = 0; m < 4; ++m) { bf16_t* rowp = O + (size_t)(row0 + ai * HALF + m * 16) * ldc + col0;
; #pragma unroll
;                 for (int bj = 0; bj < 2; ++bj) { f32x4 v0 = acc[ai][bj][m][0], v1 = acc[ai][bj][m][1];
;                     if (ACT == 1) {
; #pragma unroll
;                         for (int j = 0; j < 4; ++j) { const float a = fmaxf(v0[j], 0.f), b = fmaxf(v1[j], 0.f); v0[j] = a * a; v1[j] = b * b; } }
;                     u32x4 w; w.x = cvt_pk_bf16(v0[0], v0[1]); w.y = cvt_pk_bf16(v0[2], v0[3]); w.z = cvt_pk_bf16(v1[0], v1[1]); w.w = cvt_pk_bf16(v1[2], v1[3]);
;                     w.x = (unsigned)__builtin_amdgcn_ds_bpermute(src4, (int)w.x); w.y = (unsigned)__builtin_amdgcn_ds_bpermute(src4, (int)w.y);
;                     w.z = (unsigned)__builtin_amdgcn_ds_bpermute(src4, (int)w.z); w.w = (unsigned)__builtin_amdgcn_ds_bpermute(src4, (int)w.w);
;                     *(u32x4*)(rowp + bj * HALF) = w; } }
	global_store_dwordx4 v[112:113], v[100:103], off offset:256
	s_nop 1
	v_mul_f32_e32 v92, v92, v92
	v_mul_f32_e32 v93, v93, v93
	v_mul_f32_e32 v94, v94, v94
	v_mul_f32_e32 v99, v99, v99
	v_cvt_pk_bf16_f32 v96, v96, v97
	v_cvt_pk_bf16_f32 v97, v98, v99
	v_cvt_pk_bf16_f32 v98, v92, v93
	v_cvt_pk_bf16_f32 v95, v94, v95
	v_or_b32_e32 v100, 32, v140
	ds_bpermute_b32 v92, v143, v96
	ds_bpermute_b32 v93, v143, v97
	ds_bpermute_b32 v94, v143, v98
	ds_bpermute_b32 v95, v143, v95
	v_ashrrev_i32_e32 v101, 31, v100
	v_lshlrev_b64 v[96:97], 13, v[100:101]
	v_max_f32_e32 v88, v88, v88
	v_max_f32_e32 v89, v89, v89
	v_max_f32_e32 v90, v90, v90
	v_max_f32_e32 v87, v87, v87
	v_lshl_add_u64 v[96:97], s[12:13], 0, v[96:97]
	v_max_f32_e32 v88, 0, v88
	v_max_f32_e32 v84, v84, v84
	v_max_f32_e32 v89, 0, v89
	v_max_f32_e32 v85, v85, v85
	v_max_f32_e32 v90, 0, v90
	v_max_f32_e32 v86, v86, v86
	v_max_f32_e32 v91, v91, v91
	v_max_f32_e32 v87, 0, v87
	v_lshl_add_u64 v[96:97], v[96:97], 0, v[126:127]
	v_max_f32_e32 v84, 0, v84
	v_mul_f32_e32 v88, v88, v88
	v_max_f32_e32 v85, 0, v85
	v_mul_f32_e32 v89, v89, v89
	v_max_f32_e32 v86, 0, v86
	v_mul_f32_e32 v90, v90, v90
	v_max_f32_e32 v91, 0, v91
	v_mul_f32_e32 v87, v87, v87
	v_mul_f32_e32 v84, v84, v84
	v_mul_f32_e32 v85, v85, v85
	v_mul_f32_e32 v86, v86, v86
	v_mul_f32_e32 v91, v91, v91
	v_cvt_pk_bf16_f32 v88, v88, v89
	v_cvt_pk_bf16_f32 v89, v90, v91
	v_cvt_pk_bf16_f32 v90, v84, v85
	v_cvt_pk_bf16_f32 v87, v86, v87
	ds_bpermute_b32 v84, v143, v88
	ds_bpermute_b32 v85, v143, v89
	ds_bpermute_b32 v86, v143, v90
	ds_bpermute_b32 v87, v143, v87
	v_max_f32_e32 v80, v80, v80
	v_max_f32_e32 v81, v81, v81
	v_max_f32_e32 v82, v82, v82
	v_max_f32_e32 v79, v79, v79
	v_max_f32_e32 v80, 0, v80
	v_max_f32_e32 v76, v76, v76
	v_max_f32_e32 v81, 0, v81
	v_max_f32_e32 v77, v77, v77
	v_max_f32_e32 v82, 0, v82
	v_max_f32_e32 v78, v78, v78
	v_max_f32_e32 v83, v83, v83
	v_max_f32_e32 v79, 0, v79
	v_max_f32_e32 v76, 0, v76
	v_mul_f32_e32 v80, v80, v80
	v_max_f32_e32 v77, 0, v77
	v_mul_f32_e32 v81, v81, v81
	v_max_f32_e32 v78, 0, v78
	v_mul_f32_e32 v82, v82, v82
	v_max_f32_e32 v83, 0, v83
	v_mul_f32_e32 v79, v79, v79
	s_waitcnt lgkmcnt(4)
	global_store_dwordx4 v[96:97], v[92:95], off
	s_nop 1
	s_waitcnt lgkmcnt(0)
	global_store_dwordx4 v[96:97], v[84:87], off offset:256
	s_nop 1
	v_mul_f32_e32 v76, v76, v76
	v_mul_f32_e32 v77, v77, v77
	v_mul_f32_e32 v78, v78, v78
	v_mul_f32_e32 v83, v83, v83
	v_cvt_pk_bf16_f32 v80, v80, v81
	v_cvt_pk_bf16_f32 v81, v82, v83
	v_cvt_pk_bf16_f32 v82, v76, v77
	v_cvt_pk_bf16_f32 v79, v78, v79
	v_or_b32_e32 v84, 48, v140
	ds_bpermute_b32 v76, v143, v80
	ds_bpermute_b32 v77, v143, v81
	ds_bpermute_b32 v78, v143, v82
	ds_bpermute_b32 v79, v143, v79
	v_ashrrev_i32_e32 v85, 31, v84
	v_lshlrev_b64 v[80:81], 13, v[84:85]
	v_max_f32_e32 v72, v72, v72
	v_max_f32_e32 v73, v73, v73
	v_max_f32_e32 v74, v74, v74
	v_max_f32_e32 v71, v71, v71
	v_lshl_add_u64 v[80:81], s[12:13], 0, v[80:81]
	v_max_f32_e32 v72, 0, v72
	v_max_f32_e32 v68, v68, v68
	v_max_f32_e32 v73, 0, v73
	v_max_f32_e32 v69, v69, v69
	v_max_f32_e32 v74, 0, v74
	v_max_f32_e32 v70, v70, v70
	v_max_f32_e32 v75, v75, v75
	v_max_f32_e32 v71, 0, v71
	v_lshl_add_u64 v[80:81], v[80:81], 0, v[126:127]
	v_max_f32_e32 v68, 0, v68
	v_mul_f32_e32 v72, v72, v72
	v_max_f32_e32 v69, 0, v69
	v_mul_f32_e32 v73, v73, v73
	v_max_f32_e32 v70, 0, v70
	v_mul_f32_e32 v74, v74, v74
	v_max_f32_e32 v75, 0, v75
	v_mul_f32_e32 v71, v71, v71
	v_mul_f32_e32 v68, v68, v68
	v_mul_f32_e32 v69, v69, v69
	v_mul_f32_e32 v70, v70, v70
	v_mul_f32_e32 v75, v75, v75
	v_cvt_pk_bf16_f32 v72, v72, v73
	v_cvt_pk_bf16_f32 v73, v74, v75
	v_cvt_pk_bf16_f32 v74, v68, v69
	v_cvt_pk_bf16_f32 v71, v70, v71
	ds_bpermute_b32 v68, v143, v72
	ds_bpermute_b32 v69, v143, v73
	ds_bpermute_b32 v70, v143, v74
	ds_bpermute_b32 v71, v143, v71
	v_max_f32_e32 v64, v64, v64
	v_max_f32_e32 v65, v65, v65
	v_max_f32_e32 v66, v66, v66
	v_max_f32_e32 v63, v63, v63
	v_max_f32_e32 v64, 0, v64
	v_max_f32_e32 v60, v60, v60
	v_max_f32_e32 v65, 0, v65
	v_max_f32_e32 v61, v61, v61
	v_max_f32_e32 v66, 0, v66
	v_max_f32_e32 v62, v62, v62
	v_max_f32_e32 v67, v67, v67
	v_max_f32_e32 v63, 0, v63
	v_max_f32_e32 v60, 0, v60
	v_mul_f32_e32 v64, v64, v64
	v_max_f32_e32 v61, 0, v61
	v_mul_f32_e32 v65, v65, v65
	v_max_f32_e32 v62, 0, v62
	v_mul_f32_e32 v66, v66, v66
	v_max_f32_e32 v67, 0, v67
	v_mul_f32_e32 v63, v63, v63
	v_mul_f32_e32 v60, v60, v60
	v_mul_f32_e32 v61, v61, v61
	v_mul_f32_e32 v62, v62, v62
	v_mul_f32_e32 v67, v67, v67
	v_cvt_pk_bf16_f32 v64, v64, v65
	v_cvt_pk_bf16_f32 v65, v66, v67
	v_cvt_pk_bf16_f32 v66, v60, v61
	v_cvt_pk_bf16_f32 v63, v62, v63
	ds_bpermute_b32 v60, v143, v64
	ds_bpermute_b32 v61, v143, v65
	ds_bpermute_b32 v62, v143, v66
	ds_bpermute_b32 v63, v143, v63
	s_mov_b32 s17, 0x100000
	v_max_f32_e32 v56, v56, v56
	v_max_f32_e32 v57, v57, v57
	v_max_f32_e32 v58, v58, v58
	v_max_f32_e32 v55, v55, v55
	v_add_co_u32_e32 v64, vcc, s17, v124
	v_max_f32_e32 v56, 0, v56
	v_max_f32_e32 v52, v52, v52
	v_max_f32_e32 v57, 0, v57
	v_max_f32_e32 v53, v53, v53
	v_max_f32_e32 v58, 0, v58
	v_max_f32_e32 v54, v54, v54
	v_max_f32_e32 v59, v59, v59
	v_max_f32_e32 v55, 0, v55
	v_addc_co_u32_e32 v65, vcc, 0, v125, vcc
	v_max_f32_e32 v52, 0, v52
	v_mul_f32_e32 v56, v56, v56
	v_max_f32_e32 v53, 0, v53
	v_mul_f32_e32 v57, v57, v57
	v_max_f32_e32 v54, 0, v54
	v_mul_f32_e32 v58, v58, v58
	v_max_f32_e32 v59, 0, v59
	v_mul_f32_e32 v55, v55, v55
	s_waitcnt lgkmcnt(8)
; __device__ __forceinline__ unsigned cvt_pk_bf16(float lo, float hi) { unsigned r; asm volatile("v_cvt_pk_bf16_f32 %0, %1, %2" : "=v"(r) : "v"(lo), "v"(hi)); return r; }
;     __device__ __forceinline__ void operator()(const f32x4 (&acc)[2][2][4][2], const Unit& u, int wr, int wc, int fr, int fq) const {
;     ...
;             for (int m = 0; m < 4; ++m) { bf16_t* rowp = O + (size_t)(row0 + ai * HALF + m * 16) * ldc + col0;
; #pragma unroll
;                 for (int bj = 0; bj < 2; ++bj) { f32x4 v0 = acc[ai][bj][m][0], v1 = acc[ai][bj][m][1];
;                     if (ACT == 1) {
; #pragma unroll
;                         for (int j = 0; j < 4; ++j) { const float a = fmaxf(v0[j], 0.f), b = fmaxf(v1[j], 0.f); v0[j] = a * a; v1[j] = b * b; } }
;                     u32x4 w; w.x = cvt_pk_bf16(v0[0], v0[1]); w.y = cvt_pk_bf16(v0[2], v0[3]); w.z = cvt_pk_bf16(v1[0], v1[1]); w.w = cvt_pk_bf16(v1[2], v1[3]);
;                     w.x = (unsigned)__builtin_amdgcn_ds_bpermute(src4, (int)w.x); w.y = (unsigned)__builtin_amdgcn_ds_bpermute(src4, (int)w.y);
;                     w.z = (unsigned)__builtin_amdgcn_ds_bpermute(src4, (int)w.z); w.w = (unsigned)__builtin_amdgcn_ds_bpermute(src4, (int)w.w);
;                     *(u32x4*)(rowp + bj * HALF) = w; } }
	global_store_dwordx4 v[80:81], v[76:79], off
	s_nop 1
	v_mul_f32_e32 v52, v52, v52
	v_mul_f32_e32 v53, v53, v53
	v_mul_f32_e32 v54, v54, v54
	v_mul_f32_e32 v59, v59, v59
	v_cvt_pk_bf16_f32 v56, v56, v57
	v_cvt_pk_bf16_f32 v57, v58, v59
	v_cvt_pk_bf16_f32 v58, v52, v53
	v_cvt_pk_bf16_f32 v55, v54, v55
	ds_bpermute_b32 v52, v143, v56
	ds_bpermute_b32 v53, v143, v57
	ds_bpermute_b32 v54, v143, v58
	ds_bpermute_b32 v55, v143, v55
	v_max_f32_e32 v48, v48, v48
	v_max_f32_e32 v49, v49, v49
	v_max_f32_e32 v50, v50, v50
	v_max_f32_e32 v47, v47, v47
	s_mov_b64 s[24:25], 0x100000
	v_max_f32_e32 v48, 0, v48
	v_max_f32_e32 v44, v44, v44
	v_max_f32_e32 v49, 0, v49
	v_max_f32_e32 v45, v45, v45
	v_max_f32_e32 v50, 0, v50
	v_max_f32_e32 v46, v46, v46
	v_max_f32_e32 v51, v51, v51
	v_max_f32_e32 v47, 0, v47
	v_lshl_add_u64 v[56:57], v[124:125], 0, s[24:25]
	v_max_f32_e32 v44, 0, v44
	v_mul_f32_e32 v48, v48, v48
	v_max_f32_e32 v45, 0, v45
	v_mul_f32_e32 v49, v49, v49
	v_max_f32_e32 v46, 0, v46
	v_mul_f32_e32 v50, v50, v50
	v_max_f32_e32 v51, 0, v51
	v_mul_f32_e32 v47, v47, v47
	s_waitcnt lgkmcnt(8)
	global_store_dwordx4 v[80:81], v[68:71], off offset:256
	s_nop 1
	v_mul_f32_e32 v44, v44, v44
	v_mul_f32_e32 v45, v45, v45
	v_mul_f32_e32 v46, v46, v46
	v_mul_f32_e32 v51, v51, v51
	v_cvt_pk_bf16_f32 v48, v48, v49
	v_cvt_pk_bf16_f32 v49, v50, v51
	v_cvt_pk_bf16_f32 v50, v44, v45
	v_cvt_pk_bf16_f32 v47, v46, v47
	ds_bpermute_b32 v44, v143, v48
	ds_bpermute_b32 v45, v143, v49
	ds_bpermute_b32 v46, v143, v50
	ds_bpermute_b32 v47, v143, v47
	s_mov_b32 s17, 0x120000
	v_max_f32_e32 v40, v40, v40
	v_max_f32_e32 v41, v41, v41
	v_max_f32_e32 v42, v42, v42
	v_max_f32_e32 v39, v39, v39
	v_add_co_u32_e32 v48, vcc, s17, v124
	v_max_f32_e32 v40, 0, v40
	v_max_f32_e32 v36, v36, v36
	v_max_f32_e32 v41, 0, v41
	v_max_f32_e32 v37, v37, v37
	v_max_f32_e32 v42, 0, v42
	v_max_f32_e32 v38, v38, v38
	v_max_f32_e32 v43, v43, v43
	v_max_f32_e32 v39, 0, v39
	v_addc_co_u32_e32 v49, vcc, 0, v125, vcc
	v_max_f32_e32 v36, 0, v36
	v_mul_f32_e32 v40, v40, v40
	v_max_f32_e32 v37, 0, v37
	v_mul_f32_e32 v41, v41, v41
	v_max_f32_e32 v38, 0, v38
	v_mul_f32_e32 v42, v42, v42
	v_max_f32_e32 v43, 0, v43
	v_mul_f32_e32 v39, v39, v39
	s_waitcnt lgkmcnt(8)
	global_store_dwordx4 v[64:65], v[60:63], off
	s_nop 1
	v_mul_f32_e32 v36, v36, v36
	v_mul_f32_e32 v37, v37, v37
	v_mul_f32_e32 v38, v38, v38
	v_mul_f32_e32 v43, v43, v43
	v_cvt_pk_bf16_f32 v40, v40, v41
	v_cvt_pk_bf16_f32 v41, v42, v43
	v_cvt_pk_bf16_f32 v42, v36, v37
	v_cvt_pk_bf16_f32 v39, v38, v39
	ds_bpermute_b32 v36, v143, v40
	ds_bpermute_b32 v37, v143, v41
	ds_bpermute_b32 v38, v143, v42
	ds_bpermute_b32 v39, v143, v39
	v_max_f32_e32 v32, v32, v32
	v_max_f32_e32 v33, v33, v33
	v_max_f32_e32 v34, v34, v34
	v_max_f32_e32 v31, v31, v31
	s_mov_b64 s[24:25], 0x120000
	v_max_f32_e32 v32, 0, v32
	v_max_f32_e32 v28, v28, v28
	v_max_f32_e32 v33, 0, v33
	v_max_f32_e32 v29, v29, v29
	v_max_f32_e32 v34, 0, v34
	v_max_f32_e32 v30, v30, v30
	v_max_f32_e32 v35, v35, v35
	v_max_f32_e32 v31, 0, v31
	v_lshl_add_u64 v[40:41], v[124:125], 0, s[24:25]
	v_max_f32_e32 v28, 0, v28
	v_mul_f32_e32 v32, v32, v32
	v_max_f32_e32 v29, 0, v29
	v_mul_f32_e32 v33, v33, v33
	v_max_f32_e32 v30, 0, v30
	v_mul_f32_e32 v34, v34, v34
	v_max_f32_e32 v35, 0, v35
	v_mul_f32_e32 v31, v31, v31
	s_waitcnt lgkmcnt(8)
; __device__ __forceinline__ unsigned cvt_pk_bf16(float lo, float hi) { unsigned r; asm volatile("v_cvt_pk_bf16_f32 %0, %1, %2" : "=v"(r) : "v"(lo), "v"(hi)); return r; }
;     __device__ __forceinline__ void operator()(const f32x4 (&acc)[2][2][4][2], const Unit& u, int wr, int wc, int fr, int fq) const {
;     ...
;             for (int m = 0; m < 4; ++m) { bf16_t* rowp = O + (size_t)(row0 + ai * HALF + m * 16) * ldc + col0;
; #pragma unroll
;                 for (int bj = 0; bj < 2; ++bj) { f32x4 v0 = acc[ai][bj][m][0], v1 = acc[ai][bj][m][1];
;                     if (ACT == 1) {
; #pragma unroll
;                         for (int j = 0; j < 4; ++j) { const float a = fmaxf(v0[j], 0.f), b = fmaxf(v1[j], 0.f); v0[j] = a * a; v1[j] = b * b; } }
;                     u32x4 w; w.x = cvt_pk_bf16(v0[0], v0[1]); w.y = cvt_pk_bf16(v0[2], v0[3]); w.z = cvt_pk_bf16(v1[0], v1[1]); w.w = cvt_pk_bf16(v1[2], v1[3]);
;                     w.x = (unsigned)__builtin_amdgcn_ds_bpermute(src4, (int)w.x); w.y = (unsigned)__builtin_amdgcn_ds_bpermute(src4, (int)w.y);
;                     w.z = (unsigned)__builtin_amdgcn_ds_bpermute(src4, (int)w.z); w.w = (unsigned)__builtin_amdgcn_ds_bpermute(src4, (int)w.w);
;                     *(u32x4*)(rowp + bj * HALF) = w; } }
	global_store_dwordx4 v[56:57], v[52:55], off offset:256
	s_nop 1
	v_mul_f32_e32 v28, v28, v28
	v_mul_f32_e32 v29, v29, v29
	v_mul_f32_e32 v30, v30, v30
	v_mul_f32_e32 v35, v35, v35
	v_cvt_pk_bf16_f32 v32, v32, v33
	v_cvt_pk_bf16_f32 v33, v34, v35
	v_cvt_pk_bf16_f32 v34, v28, v29
	v_cvt_pk_bf16_f32 v31, v30, v31
	ds_bpermute_b32 v28, v143, v32
	ds_bpermute_b32 v29, v143, v33
	ds_bpermute_b32 v30, v143, v34
	ds_bpermute_b32 v31, v143, v31
	s_mov_b32 s17, 0x140000
	v_max_f32_e32 v24, v24, v24
	v_max_f32_e32 v25, v25, v25
	v_max_f32_e32 v26, v26, v26
	v_max_f32_e32 v23, v23, v23
	v_add_co_u32_e32 v32, vcc, s17, v124
	v_max_f32_e32 v24, 0, v24
	v_max_f32_e32 v20, v20, v20
	v_max_f32_e32 v25, 0, v25
	v_max_f32_e32 v21, v21, v21
	v_max_f32_e32 v26, 0, v26
	v_max_f32_e32 v22, v22, v22
	v_max_f32_e32 v27, v27, v27
	v_max_f32_e32 v23, 0, v23
	v_addc_co_u32_e32 v33, vcc, 0, v125, vcc
	v_max_f32_e32 v20, 0, v20
	v_mul_f32_e32 v24, v24, v24
	v_max_f32_e32 v21, 0, v21
	v_mul_f32_e32 v25, v25, v25
	v_max_f32_e32 v22, 0, v22
	v_mul_f32_e32 v26, v26, v26
	v_max_f32_e32 v27, 0, v27
	v_mul_f32_e32 v23, v23, v23
	s_waitcnt lgkmcnt(8)
	global_store_dwordx4 v[48:49], v[44:47], off
	s_nop 1
	v_mul_f32_e32 v20, v20, v20
	v_mul_f32_e32 v21, v21, v21
	v_mul_f32_e32 v22, v22, v22
	v_mul_f32_e32 v27, v27, v27
	v_cvt_pk_bf16_f32 v24, v24, v25
	v_cvt_pk_bf16_f32 v25, v26, v27
	v_cvt_pk_bf16_f32 v26, v20, v21
	v_cvt_pk_bf16_f32 v23, v22, v23
	ds_bpermute_b32 v20, v143, v24
	ds_bpermute_b32 v21, v143, v25
	ds_bpermute_b32 v22, v143, v26
	ds_bpermute_b32 v23, v143, v23
	v_max_f32_e32 v16, v16, v16
	v_max_f32_e32 v17, v17, v17
	v_max_f32_e32 v18, v18, v18
	v_max_f32_e32 v15, v15, v15
	s_mov_b64 s[24:25], 0x140000
	v_max_f32_e32 v16, 0, v16
	v_max_f32_e32 v12, v12, v12
	v_max_f32_e32 v17, 0, v17
	v_max_f32_e32 v13, v13, v13
	v_max_f32_e32 v18, 0, v18
	v_max_f32_e32 v14, v14, v14
	v_max_f32_e32 v19, v19, v19
	v_max_f32_e32 v15, 0, v15
	v_lshl_add_u64 v[24:25], v[124:125], 0, s[24:25]
	v_max_f32_e32 v12, 0, v12
	v_mul_f32_e32 v16, v16, v16
	v_max_f32_e32 v13, 0, v13
	v_mul_f32_e32 v17, v17, v17
	v_max_f32_e32 v14, 0, v14
	v_mul_f32_e32 v18, v18, v18
	v_max_f32_e32 v19, 0, v19
	v_mul_f32_e32 v15, v15, v15
	s_waitcnt lgkmcnt(8)
	global_store_dwordx4 v[40:41], v[36:39], off offset:256
	s_nop 1
	v_mul_f32_e32 v12, v12, v12
	v_mul_f32_e32 v13, v13, v13
	v_mul_f32_e32 v14, v14, v14
	v_mul_f32_e32 v19, v19, v19
	v_cvt_pk_bf16_f32 v16, v16, v17
	v_cvt_pk_bf16_f32 v17, v18, v19
	v_cvt_pk_bf16_f32 v18, v12, v13
	v_cvt_pk_bf16_f32 v15, v14, v15
	ds_bpermute_b32 v12, v143, v16
	ds_bpermute_b32 v13, v143, v17
	ds_bpermute_b32 v14, v143, v18
	ds_bpermute_b32 v15, v143, v15
	s_mov_b32 s17, 0x160000
	v_max_f32_e32 v4, v4, v4
	v_max_f32_e32 v5, v5, v5
	v_max_f32_e32 v6, v6, v6
	v_max_f32_e32 v3, v3, v3
	v_add_co_u32_e32 v16, vcc, s17, v124
	v_max_f32_e32 v4, 0, v4
	v_max_f32_e32 v0, v0, v0
	v_max_f32_e32 v5, 0, v5
	v_max_f32_e32 v1, v1, v1
	v_max_f32_e32 v6, 0, v6
	v_max_f32_e32 v2, v2, v2
	v_max_f32_e32 v7, v7, v7
	v_max_f32_e32 v3, 0, v3
	v_addc_co_u32_e32 v17, vcc, 0, v125, vcc
	v_max_f32_e32 v0, 0, v0
	v_mul_f32_e32 v4, v4, v4
	v_max_f32_e32 v1, 0, v1
	v_mul_f32_e32 v5, v5, v5
	v_max_f32_e32 v2, 0, v2
	v_mul_f32_e32 v6, v6, v6
	v_max_f32_e32 v7, 0, v7
	v_mul_f32_e32 v3, v3, v3
	s_waitcnt lgkmcnt(8)
	global_store_dwordx4 v[32:33], v[28:31], off
	s_nop 1
	v_mul_f32_e32 v0, v0, v0
	v_mul_f32_e32 v1, v1, v1
	v_mul_f32_e32 v2, v2, v2
	v_mul_f32_e32 v7, v7, v7
	v_cvt_pk_bf16_f32 v4, v4, v5
	v_cvt_pk_bf16_f32 v5, v6, v7
	v_cvt_pk_bf16_f32 v6, v0, v1
	v_cvt_pk_bf16_f32 v3, v2, v3
	ds_bpermute_b32 v0, v143, v4
	ds_bpermute_b32 v1, v143, v5
	ds_bpermute_b32 v2, v143, v6
	ds_bpermute_b32 v3, v143, v3
	s_mov_b64 s[24:25], 0x160000
	v_lshl_add_u64 v[4:5], v[124:125], 0, s[24:25]
	s_andn2_b64 vcc, exec, s[6:7]
	s_mov_b64 s[6:7], -1
	s_waitcnt lgkmcnt(8)
	global_store_dwordx4 v[24:25], v[20:23], off offset:256
	s_nop 1
	s_waitcnt lgkmcnt(4)
	global_store_dwordx4 v[16:17], v[12:15], off
	s_nop 1
	s_waitcnt lgkmcnt(0)
	global_store_dwordx4 v[4:5], v[0:3], off offset:256
	s_nop 1
	s_cbranch_vccnz .LBB0_1186
	s_andn2_b64 vcc, exec, s[10:11]
	s_cbranch_vccnz .LBB0_1185
	s_barrier
	s_branch .LBB0_1185
